# code placement: one s_nop before the attention tile loop (shifts the loop and all later code by 4 bytes)
# baseline (speedup 1.0000x reference)
.LBB0_998:
	s_or_b64 exec, exec, s[12:13]
	s_waitcnt vmcnt(0)
	v_mov_b32_e32 v24, v161
	v_mov_b32_e32 v25, v161
	v_mov_b32_e32 v26, v161
	v_mov_b32_e32 v27, v161
	s_lshl_b32 s9, s26, 12
	v_mov_b64_e32 v[30:31], v[26:27]
	v_mov_b64_e32 v[38:39], v[26:27]
	v_mov_b64_e32 v[42:43], v[26:27]
	v_mov_b64_e32 v[46:47], v[26:27]
	v_mov_b64_e32 v[50:51], v[26:27]
	v_mov_b64_e32 v[54:55], v[26:27]
	v_mov_b64_e32 v[58:59], v[26:27]
	v_mov_b64_e32 v[62:63], v[26:27]
	v_mov_b64_e32 v[34:35], v[26:27]
	s_waitcnt vmcnt(0)
	v_mov_b64_e32 v[16:17], v[24:25]
	v_mov_b64_e32 v[20:21], v[24:25]
	v_mov_b64_e32 v[8:9], v[24:25]
	v_mov_b64_e32 v[12:13], v[24:25]
	v_mov_b64_e32 v[0:1], v[24:25]
	v_mov_b64_e32 v[4:5], v[24:25]
	v_ashrrev_i32_e32 v153, 31, v152
	v_ashrrev_i32_e32 v151, 31, v150
	v_mov_b32_e32 v159, v161
	v_mov_b32_e32 v173, v161
	v_mov_b32_e32 v175, v161
	s_add_i32 s13, s9, 0xffffff40
	v_mov_b32_e32 v177, v161
	v_mov_b32_e32 v179, v161
	s_add_i32 s26, s27, 1
	s_add_i32 s27, s8, 64
	s_mov_b32 s29, 0
	v_mov_b32_e32 v154, 0
	v_mov_b32_e32 v203, 0xf149f2ca
	v_mov_b64_e32 v[28:29], v[24:25]
	v_mov_b64_e32 v[36:37], v[24:25]
	v_mov_b64_e32 v[40:41], v[24:25]
	v_mov_b64_e32 v[44:45], v[24:25]
	v_mov_b64_e32 v[48:49], v[24:25]
	v_mov_b64_e32 v[52:53], v[24:25]
	v_mov_b64_e32 v[56:57], v[24:25]
	v_mov_b64_e32 v[60:61], v[24:25]
	v_mov_b32_e32 v162, 0xf149f2ca
	v_mov_b32_e32 v156, 0
	v_mov_b64_e32 v[32:33], v[24:25]
	v_mov_b64_e32 v[18:19], v[26:27]
	v_mov_b64_e32 v[22:23], v[26:27]
	v_mov_b64_e32 v[10:11], v[26:27]
	v_mov_b64_e32 v[14:15], v[26:27]
	v_mov_b64_e32 v[2:3], v[26:27]
	v_mov_b64_e32 v[6:7], v[26:27]
	s_waitcnt lgkmcnt(0)
	s_barrier
	v_mul_f32_e32 v157, 0xbdd53b94, v162
	v_mul_f32_e32 v155, 0xbdd53b94, v203
	s_nop 0
